# removed m0 save/restore pairs around the 5 per-step LDS-DMA issues in the attention main loop (on top of v48)
# baseline (speedup 1.0000x reference)
; __device__ __forceinline__ int v_rd_base(int lane) { return ((lane & 3) << 3) | (((lane >> 2) & 3) << 6) | (((lane >> 4) & 1) << 5) | (((lane >> 5) & 1) << 8); }
; #define DMA_K(t, slot) do { glds16(ksrc[0] + (long)(t) * 65536, (unsigned)__builtin_amdgcn_readfirstlane(kdst + (slot) * SHM_K)); \
;     glds16(ksrc[1] + (long)(t) * 65536, (unsigned)__builtin_amdgcn_readfirstlane(kdst + (slot) * SHM_K + 1024)); \
;     glds16(krsrc + (long)(t) * 4096, (unsigned)__builtin_amdgcn_readfirstlane(krdst + (slot) * SHM_KR)); } while (0)
; #define WAIT_BAR(N) asm volatile("s_waitcnt vmcnt(" #N ") lgkmcnt(0)\n\ts_barrier" ::: "memory")
; __device__ __forceinline__ void qkt(f32x16& p0, f32x16& p1, const char* Ks, const char* Krs, const bf16x8* qr, const char* qro, int r32, int hi, const f32x16& negm) {
;     p0 = negm; p1 = negm;
; #pragma unroll
;     for (int d0 = 0; d0 < 8; ++d0) { const int cb = (d0 * 16 + hi * 8) * 2;
;         const bf16x8 b0 = *reinterpret_cast<const bf16x8*>(Ks + KSWZ(r32, cb));
;         const bf16x8 b1 = *reinterpret_cast<const bf16x8*>(Ks + KSWZ(32 + r32, cb));
;         p0 = __builtin_amdgcn_mfma_f32_32x32x16_bf16(b0, qr[d0], p0, 0, 0, 0);
;         p1 = __builtin_amdgcn_mfma_f32_32x32x16_bf16(b1, qr[d0], p1, 0, 0, 0); }
; #pragma unroll
;     for (int d0 = 0; d0 < 4; ++d0) { const int cb = (d0 * 16 + hi * 8) * 2;
;         const bf16x8 b0 = *reinterpret_cast<const bf16x8*>(Krs + KRSWZ(r32, cb));
;         const bf16x8 b1 = *reinterpret_cast<const bf16x8*>(Krs + KRSWZ(32 + r32, cb));
;         const bf16x8 qf = qr[8 + d0];
;         p0 = __builtin_amdgcn_mfma_f32_32x32x16_bf16(b0, qf, p0, 0, 0, 0);
;         p1 = __builtin_amdgcn_mfma_f32_32x32x16_bf16(b1, qf, p1, 0, 0, 0); }
; }
; __device__ __forceinline__ void attn_unit(const bf16_t* __restrict__ Qb, const bf16_t* __restrict__ Kh, const bf16_t* __restrict__ Vh, const bf16_t* __restrict__ Krh, ...
;     ...
;     const int vb0 = (int)(uintptr_t)V_lds + v_rd_base(lane);
;     const int NT = seq / 64;
;     ...
;     f32x16 p0, p1; float al = 1.f, mn_; bf16x8 pa0, pa1, pa2, pa3;
;     asm volatile("s_waitcnt vmcnt(0) lgkmcnt(0)" ::: "memory");
;     DMA_K(0, 0); DMA_V(0, 0); DMA_K(1, 1);
;     WAIT_BAR(0);
;     int s0 = 2, s1 = 0, s2 = 1;
;     for (int j = 0; j < NT; ++j) {
;         if (j + 1 < NT) DMA_V(j + 1, s2);
;         if (j + 2 < NT) DMA_K(j + 2, s0);
.LBB0_396:
	s_mov_b32 s6, s70
	s_lshl_b32 s7, s6, 14
	s_add_i32 s10, s7, 0
	v_add3_u32 v68, s10, v227, v211
	ds_read_b128 v[64:67], v68
	s_lshl_b32 s74, vcc_lo, 14
	v_add_u32_e32 v245, s74, v228
	s_lshl_b32 s72, s71, 14
	v_readfirstlane_b32 s100, v245
	s_nop 0
	s_mov_b32 m0, s100
	s_nop 0
	global_load_lds_dwordx4 v[208:209], off
	s_addk_i32 s100, 0x400
	v_add_u32_e32 v245, s72, v213
	s_mov_b32 m0, s100
	s_nop 0
	global_load_lds_dwordx4 v[206:207], off
	s_lshl_b32 s73, s71, 13
	v_readfirstlane_b32 s100, v245
	s_nop 0
	s_mov_b32 m0, s100
	s_nop 0
	global_load_lds_dwordx4 v[204:205], off
	s_addk_i32 s100, 0x400
	v_add_u32_e32 v245, s73, v212
	s_mov_b32 m0, s100
	s_nop 0
	global_load_lds_dwordx4 v[202:203], off
	v_readfirstlane_b32 s100, v245
	s_nop 0
	s_mov_b32 m0, s100
	s_nop 0
	global_load_lds_dwordx4 v[200:201], off
	s_waitcnt lgkmcnt(0)
	v_mfma_f32_32x32x16_bf16 v[112:127], v[64:67], v[128:131], v[80:95]
	ds_read_b128 v[64:67], v68 offset:8192
	v_add3_u32 v68, s10, v226, v211
	s_lshl_b32 s11, s6, 13
	s_mov_b32 s70, vcc_lo
	s_waitcnt lgkmcnt(0)
	v_mfma_f32_32x32x16_bf16 v[96:111], v[64:67], v[128:131], v[80:95]
	ds_read_b128 v[64:67], v68
	s_waitcnt lgkmcnt(0)
	v_mfma_f32_32x32x16_bf16 v[112:127], v[64:67], v[132:135], v[112:127]
	ds_read_b128 v[64:67], v68 offset:8192
	v_add3_u32 v68, s10, v225, v211
	s_waitcnt lgkmcnt(0)
	v_mfma_f32_32x32x16_bf16 v[96:111], v[64:67], v[132:135], v[96:111]
	ds_read_b128 v[64:67], v68
	s_waitcnt lgkmcnt(0)
	v_mfma_f32_32x32x16_bf16 v[112:127], v[64:67], v[136:139], v[112:127]
	ds_read_b128 v[64:67], v68 offset:8192
	v_add3_u32 v68, s10, v224, v211
	s_waitcnt lgkmcnt(0)
	v_mfma_f32_32x32x16_bf16 v[96:111], v[64:67], v[136:139], v[96:111]
	ds_read_b128 v[64:67], v68
	s_waitcnt lgkmcnt(0)
	v_mfma_f32_32x32x16_bf16 v[112:127], v[64:67], v[140:143], v[112:127]
	ds_read_b128 v[64:67], v68 offset:8192
	v_add3_u32 v68, s10, v223, v211
	s_waitcnt lgkmcnt(0)
	v_mfma_f32_32x32x16_bf16 v[96:111], v[64:67], v[140:143], v[96:111]
	ds_read_b128 v[64:67], v68
	s_waitcnt lgkmcnt(0)
	v_mfma_f32_32x32x16_bf16 v[112:127], v[64:67], v[144:147], v[112:127]
	ds_read_b128 v[64:67], v68 offset:8192
	v_add3_u32 v68, s10, v222, v211
	s_waitcnt lgkmcnt(0)
	v_mfma_f32_32x32x16_bf16 v[96:111], v[64:67], v[144:147], v[96:111]
	ds_read_b128 v[64:67], v68
	s_waitcnt lgkmcnt(0)
	v_mfma_f32_32x32x16_bf16 v[112:127], v[64:67], v[148:151], v[112:127]
	ds_read_b128 v[64:67], v68 offset:8192
	v_add3_u32 v68, s10, v221, v211
	s_waitcnt lgkmcnt(0)
	v_mfma_f32_32x32x16_bf16 v[96:111], v[64:67], v[148:151], v[96:111]
	ds_read_b128 v[64:67], v68
	s_waitcnt lgkmcnt(0)
	v_mfma_f32_32x32x16_bf16 v[112:127], v[64:67], v[152:155], v[112:127]
	ds_read_b128 v[64:67], v68 offset:8192
	v_add3_u32 v68, s10, v220, v211
	s_sub_i32 s10, s10, s11
	s_waitcnt lgkmcnt(0)
	v_mfma_f32_32x32x16_bf16 v[96:111], v[64:67], v[152:155], v[96:111]
	ds_read_b128 v[64:67], v68
	s_waitcnt lgkmcnt(0)
	v_mfma_f32_32x32x16_bf16 v[112:127], v[64:67], v[156:159], v[112:127]
	ds_read_b128 v[64:67], v68 offset:8192
	v_add3_u32 v68, s10, v219, v215
	s_waitcnt lgkmcnt(0)
	v_mfma_f32_32x32x16_bf16 v[96:111], v[64:67], v[156:159], v[96:111]
	ds_read_b128 v[64:67], v68 offset:49152
	s_waitcnt lgkmcnt(0)
	v_mfma_f32_32x32x16_bf16 v[112:127], v[64:67], v[164:167], v[112:127]
	ds_read_b128 v[64:67], v68 offset:53248
	v_add3_u32 v68, s10, v218, v215
	s_waitcnt lgkmcnt(0)
	v_mfma_f32_32x32x16_bf16 v[96:111], v[64:67], v[164:167], v[96:111]
	ds_read_b128 v[64:67], v68 offset:49152
	s_waitcnt lgkmcnt(0)
	v_mfma_f32_32x32x16_bf16 v[112:127], v[64:67], v[172:175], v[112:127]
	ds_read_b128 v[64:67], v68 offset:53248
	v_add3_u32 v68, s10, v217, v215
	s_waitcnt lgkmcnt(0)
	v_mfma_f32_32x32x16_bf16 v[96:111], v[64:67], v[172:175], v[96:111]
	ds_read_b128 v[64:67], v68 offset:49152
	s_waitcnt lgkmcnt(0)
	v_mfma_f32_32x32x16_bf16 v[112:127], v[64:67], v[160:163], v[112:127]
	ds_read_b128 v[64:67], v68 offset:53248
	v_add3_u32 v68, s10, v216, v215
	s_waitcnt lgkmcnt(0)
	v_mfma_f32_32x32x16_bf16 v[96:111], v[64:67], v[160:163], v[96:111]
	ds_read_b128 v[64:67], v68 offset:49152
	s_waitcnt lgkmcnt(0)
	v_mfma_f32_32x32x16_bf16 v[112:127], v[64:67], v[168:171], v[112:127]
	ds_read_b128 v[64:67], v68 offset:53248
	s_waitcnt lgkmcnt(0)
	v_mfma_f32_32x32x16_bf16 v[96:111], v[64:67], v[168:171], v[96:111]
	s_nop 8
	v_max_f32_e32 v68, v113, v113
	v_max_f32_e32 v69, v112, v112
	v_max_f32_e32 v68, v69, v68
	v_max_f32_e32 v69, v121, v121
	v_max_f32_e32 v70, v120, v120
	v_max_f32_e32 v69, v70, v69
	v_max3_f32 v66, v68, v114, v115
	v_max_f32_e32 v64, v105, v105
	v_max_f32_e32 v65, v104, v104
	v_max_f32_e32 v64, v65, v64
	v_max3_f32 v65, v96, v97, v98
	v_max3_f32 v64, v64, v106, v107
	v_max3_f32 v67, v69, v122, v123
	v_max3_f32 v65, v65, v99, v100
	v_max3_f32 v64, v64, v108, v109
	v_max3_f32 v66, v66, v116, v117
	v_max3_f32 v67, v67, v124, v125
	v_max3_f32 v65, v65, v101, v102
	v_max3_f32 v64, v64, v110, v111
	v_max3_f32 v66, v66, v118, v119
	v_max3_f32 v67, v67, v126, v127
	v_max3_f32 v64, v65, v103, v64
	v_max3_f32 v64, v66, v67, v64
	v_mov_b32_e32 v65, v64
	s_nop 1
	v_permlane32_swap_b32_e32 v64, v65
	v_max_f32_e32 v65, v65, v65
	v_max_f32_e32 v64, v64, v64
	v_max_f32_e32 v64, v64, v65
	v_cmp_ge_f32_e32 vcc, s92, v64
	s_cmp_eq_u64 vcc, exec
	s_cbranch_scc0 .LBB0_404
	v_mov_b32_e32 v229, 1.0
